# fused-norm GEMM phases: first K-tile LDS-DMA issued before the row-tile scan and row-scale table loads (cold round trips overlapped)
# speedup vs baseline: 1.0010x; 1.0010x over previous
; #define PG8_STAGE(bufoff, gbase, voff) do { _Pragma("unroll") for (int _i = 0; _i < 2; ++_i) \
;         __builtin_amdgcn_global_load_lds((const unsigned*)((const char*)(gbase) + (voff)[_i]), (PG8_LAS unsigned*)(lds + (bufoff) + ldsw + _i * 8192), 16, 0, 0); } while (0)
; template <class Epi, class Sched, bool ALIGN_EPI = false, bool SP2 = false>
; __device__ __forceinline__ void gemm_phase(PG8_LAS unsigned char* lds, const Gemm g, const Sched& S, const Epi& E) {
;     const int tid = threadIdx.x, wid = __builtin_amdgcn_readfirstlane(tid >> 6), lane = tid & 63, wr = wid >> 2, wc = wid & 3, fr = lane & 15, fq = lane >> 4;
;     const int K = g.K, nt = K / BK;
;     unsigned voffA[2], voffB[2];
; #pragma unroll
;     for (int i = 0; i < 2; ++i) { int R, C; stage_rc(tid * 16 + i * 8192, R, C); const int Rb = Epi::PERM ? ((R & ~31) + perm32(R & 31)) : R;
;         voffA[i] = (unsigned)(R * K + C) * 2u; voffB[i] = (unsigned)(Rb * K + C) * 2u; }
;     const size_t kstep = (size_t)(BK * 2);
;     const size_t hstep = (size_t)HALF * K * 2;
;     const size_t tstep = 2 * hstep;
;     const unsigned ldsw = (unsigned)wid * 1024u;
;     const int aoff = lds_byte(wr * 64 + fr, fq * 8), boff = lds_byte(wc * 32 + fr, fq * 8);
;     ...
;     Unit cur, nxt; int ui = 0;
;     if (!S.next(0, cur)) return;
;     f32x4 acc[2][2][4][2];
; #pragma unroll
;     for (int a = 0; a < 2; ++a)
; #pragma unroll
;         for (int b = 0; b < 2; ++b)
; #pragma unroll
;             for (int m = 0; m < 4; ++m)
; #pragma unroll
;                 for (int n = 0; n < 2; ++n) acc[a][b][m][n] = (f32x4){0.f, 0.f, 0.f, 0.f};
;     bf16x8 At[4][2], B0[2][2], B1[2][2];
;     const char* cA = (const char*)g.A + (size_t)cur.pm * tstep; const char* cB = (const char*)g.Bt + (size_t)cur.pn * tstep;
;     S.a_ready(cur);
;     if constexpr (SP2) {
;         PG8_STAGE(PG8_SB(0, 0), cB, voffB); PG8_STAGE(PG8_SB(0, 1), cB + hstep, voffB); PG8_STAGE(PG8_SA(0, 0), cA, voffA); PG8_STAGE(PG8_SA(0, 1), cA + hstep, voffA);
.LBB0_196:
	s_cmp_lt_i32 s30, 2
	s_cselect_b64 s[4:5], -1, 0
	s_add_u32 s36, s28, 0x6800000
	s_addc_u32 s37, s29, 0
	s_add_u32 s40, s28, 0xa800000
	s_addc_u32 s41, s29, 0
	s_and_b64 s[6:7], s[4:5], s[0:1]
	s_andn2_b64 vcc, exec, s[6:7]
	s_cbranch_vccnz .LBB0_231
	s_ashr_i32 s3, s2, 31
	s_cmpk_lt_i32 s2, 0xb00
	s_cbranch_scc0 .Lpro_skip_0
	v_readfirstlane_b32 s5, v197
	s_nop 3
	v_lshrrev_b32_e32 v0, 5, v197
	v_lshrrev_b32_e32 v2, 1, v197
	v_and_b32_e32 v0, 4, v0
	v_bfe_u32 v1, v197, 2, 2
	v_and_b32_e32 v11, 24, v2
	v_or3_b32 v0, v0, v1, v11
	v_lshlrev_b32_e32 v1, 4, v197
	v_add_u32_e32 v8, 0x2000, v1
	v_lshrrev_b32_e32 v2, 7, v8
	s_movk_i32 s0, 0xe0
	v_and_b32_e32 v4, 32, v197
	v_and_or_b32 v3, v2, s0, v0
	v_bitop3_b32 v9, v1, v4, 48 bitop3:0x6c
	v_and_b32_e32 v10, 64, v197
	v_bfe_u32 v12, v197, 2, 4
	s_movk_i32 s0, 0xf0
	v_or_b32_e32 v1, v9, v10
	v_and_or_b32 v2, v2, s0, v12
	v_lshl_or_b32 v130, v2, 11, v1
	v_lshrrev_b32_e32 v2, 3, v197
	s_movk_i32 s0, 0x60
	s_add_u32 s53, s28, 0x800000
	v_and_or_b32 v0, v2, s0, v0
	s_movk_i32 s0, 0x70
	s_addc_u32 s54, s29, 0
	v_lshl_or_b32 v132, v0, 11, v1
	v_and_or_b32 v0, v2, s0, v12
	s_lshr_b32 s0, s3, 29
	s_add_i32 s0, s2, s0
	s_lshr_b32 s8, s5, 6
	s_ashr_i32 s1, s0, 3
	s_and_b32 s0, s0, -8
	s_lshr_b32 s12, s5, 8
	s_lshl_b32 s55, s8, 10
	s_sub_i32 s0, s2, s0
	s_cmp_lt_i32 s0, 0
	s_movk_i32 s56, 0x161
	s_cselect_b32 s4, s56, 0x160
	s_mul_i32 s0, s4, s0
	s_add_i32 s0, s0, s1
	s_mul_hi_i32 s1, s0, 0x2e8ba2e9
	s_lshr_b32 s4, s1, 31
	s_ashr_i32 s1, s1, 5
	s_add_i32 s1, s1, s4
	s_lshl_b32 s9, s1, 3
	s_mulk_i32 s1, 0xb0
	s_sub_i32 s0, s0, s1
	s_sext_i32_i16 s1, s0
	s_bfe_u32 s1, s1, 0x3001c
	s_add_i32 s1, s0, s1
	s_sext_i32_i16 s4, s1
	s_and_b32 s1, s1, 0xfff8
	s_sub_i32 s0, s0, s1
	s_sext_i32_i16 s0, s0
	s_lshr_b32 s4, s4, 3
	s_add_i32 s34, s9, s0
	s_ashr_i32 s35, s34, 31
	s_bfe_i64 s[10:11], s[4:5], 0x100000
	s_lshl_b64 s[0:1], s[34:35], 19
	s_lshl_b64 s[10:11], s[10:11], 19
	s_add_u32 s42, s53, s10
	s_addc_u32 s43, s54, s11
	s_add_i32 s35, s55, 0
	s_add_i32 m0, s35, 0x10000
	v_lshl_or_b32 v128, v3, 11, v1
	global_load_lds_dwordx4 v132, s[42:43]
	s_add_i32 m0, s35, 0x12000
	s_add_u32 s10, s42, 0x40000
	global_load_lds_dwordx4 v128, s[42:43]
	s_addc_u32 s11, s43, 0
	s_add_i32 m0, s35, 0x14000
	v_lshl_or_b32 v134, v0, 11, v1
	global_load_lds_dwordx4 v132, s[10:11]
	s_add_i32 m0, s35, 0x16000
	s_add_u32 s20, s36, s0
	s_addc_u32 s21, s37, s1
	s_add_i32 s57, s35, 0x2000
	global_load_lds_dwordx4 v128, s[10:11]
	s_mov_b32 m0, s35
	s_add_u32 s0, s20, 0x40000
	global_load_lds_dwordx4 v134, s[20:21]
	s_mov_b32 m0, s57
	s_addc_u32 s1, s21, 0
	s_add_i32 s58, s35, 0x4000
	global_load_lds_dwordx4 v130, s[20:21]
	s_mov_b32 m0, s58
	s_add_i32 s59, s35, 0x6000
	global_load_lds_dwordx4 v134, s[0:1]
	s_mov_b32 m0, s59
	v_mov_b32_e32 v133, 0
	global_load_lds_dwordx4 v130, s[0:1]
	s_mov_b32 s98, s12
	s_mov_b32 s99, s4
	s_mov_b32 s100, s8
	v_mov_b32_e32 v240, v10
	v_mov_b32_e32 v241, v11
	v_mov_b32_e32 v242, v12
	v_mov_b32_e32 v243, v8
	v_mov_b32_e32 v244, v9
.Lpro_skip_0:
	s_ashr_i32 s48, s22, 31
	s_mov_b32 s49, s22
	s_mov_b32 s50, -1
	s_mov_b32 s4, 16
	v_mov_b64_e32 v[0:1], 0xaff
	s_mov_b64 s[0:1], s[2:3]
	s_mov_b32 s52, -1
	s_mov_b32 s51, -1
	s_mov_b32 s12, -1
	s_branch .LBB0_200

; #define PG8_STAGE(bufoff, gbase, voff) do { _Pragma("unroll") for (int _i = 0; _i < 2; ++_i) \
;         __builtin_amdgcn_global_load_lds((const unsigned*)((const char*)(gbase) + (voff)[_i]), (PG8_LAS unsigned*)(lds + (bufoff) + ldsw + _i * 8192), 16, 0, 0); } while (0)
; #define PG8_WAIT_V(n) asm volatile("s_waitcnt vmcnt(" #n ")" ::: "memory")
; #define PG8_BAR __builtin_amdgcn_s_barrier()
; template <class Epi, class Sched, bool ALIGN_EPI = false, bool SP2 = false>
; __device__ __forceinline__ void gemm_phase(PG8_LAS unsigned char* lds, const Gemm g, const Sched& S, const Epi& E) {
;     ...
;         PG8_STAGE(PG8_SB(0, 0), cB, voffB); PG8_STAGE(PG8_SB(0, 1), cB + hstep, voffB); PG8_STAGE(PG8_SA(0, 0), cA, voffA); PG8_STAGE(PG8_SA(0, 1), cA + hstep, voffA);
;         if (wr == 1) PG8_BAR;
;         PG8_WAIT_V(2); PG8_BAR;
.LBB0_215:
	s_or_b64 exec, exec, s[4:5]
	s_cmpk_lt_i32 s2, 0xb00
	v_readfirstlane_b32 s5, v197
	s_waitcnt lgkmcnt(0)
	s_barrier
	s_cbranch_scc0 .LBB0_231
	s_mov_b32 s12, s98
	s_mov_b32 s4, s99
	s_mov_b32 s8, s100
	v_mov_b32_e32 v10, v240
	v_mov_b32_e32 v11, v241
	v_mov_b32_e32 v12, v242
	v_mov_b32_e32 v8, v243
	v_mov_b32_e32 v9, v244
	v_mov_b32_e32 v129, v133
	v_mov_b32_e32 v135, v133
	v_mov_b32_e32 v131, v133
	s_cmp_eq_u32 s12, 1
	s_mov_b32 s60, 0
	v_lshl_add_u64 v[6:7], s[42:43], 0, v[132:133]
	v_lshl_add_u64 v[4:5], s[42:43], 0, v[128:129]
	v_lshl_add_u64 v[0:1], s[20:21], 0, v[134:135]
	s_cselect_b64 s[0:1], -1, 0
	s_cmp_lg_u32 s12, 1
	v_lshl_add_u64 v[2:3], s[20:21], 0, v[130:131]
	s_cbranch_scc1 .LBB0_218
	s_barrier

; #define PG8_STAGE(bufoff, gbase, voff) do { _Pragma("unroll") for (int _i = 0; _i < 2; ++_i) \
;         __builtin_amdgcn_global_load_lds((const unsigned*)((const char*)(gbase) + (voff)[_i]), (PG8_LAS unsigned*)(lds + (bufoff) + ldsw + _i * 8192), 16, 0, 0); } while (0)
; template <class Epi, class Sched, bool ALIGN_EPI = false, bool SP2 = false>
; __device__ __forceinline__ void gemm_phase(PG8_LAS unsigned char* lds, const Gemm g, const Sched& S, const Epi& E) {
;     const int tid = threadIdx.x, wid = __builtin_amdgcn_readfirstlane(tid >> 6), lane = tid & 63, wr = wid >> 2, wc = wid & 3, fr = lane & 15, fq = lane >> 4;
;     const int K = g.K, nt = K / BK;
;     unsigned voffA[2], voffB[2];
; #pragma unroll
;     for (int i = 0; i < 2; ++i) { int R, C; stage_rc(tid * 16 + i * 8192, R, C); const int Rb = Epi::PERM ? ((R & ~31) + perm32(R & 31)) : R;
;         voffA[i] = (unsigned)(R * K + C) * 2u; voffB[i] = (unsigned)(Rb * K + C) * 2u; }
;     const size_t kstep = (size_t)(BK * 2);
;     const size_t hstep = (size_t)HALF * K * 2;
;     const size_t tstep = 2 * hstep;
;     const unsigned ldsw = (unsigned)wid * 1024u;
;     const int aoff = lds_byte(wr * 64 + fr, fq * 8), boff = lds_byte(wc * 32 + fr, fq * 8);
;     ...
;     Unit cur, nxt; int ui = 0;
;     if (!S.next(0, cur)) return;
;     f32x4 acc[2][2][4][2];
; #pragma unroll
;     for (int a = 0; a < 2; ++a)
; #pragma unroll
;         for (int b = 0; b < 2; ++b)
; #pragma unroll
;             for (int m = 0; m < 4; ++m)
; #pragma unroll
;                 for (int n = 0; n < 2; ++n) acc[a][b][m][n] = (f32x4){0.f, 0.f, 0.f, 0.f};
;     bf16x8 At[4][2], B0[2][2], B1[2][2];
;     const char* cA = (const char*)g.A + (size_t)cur.pm * tstep; const char* cB = (const char*)g.Bt + (size_t)cur.pn * tstep;
;     S.a_ready(cur);
;     if constexpr (SP2) {
;         PG8_STAGE(PG8_SB(0, 0), cB, voffB); PG8_STAGE(PG8_SB(0, 1), cB + hstep, voffB); PG8_STAGE(PG8_SA(0, 0), cA, voffA); PG8_STAGE(PG8_SA(0, 1), cA + hstep, voffA);
; __global__ void __launch_bounds__(NTHREADS, 2) mega_fwd(Args a) {
;     ...
;     if (IN(3)) { BUILD_RTAB(RT, T, 1536, false, 1) EpiWin E{VC, US, RT}; run_gemm(lds, XB, (const bf16_t*)(ws + WS_WIN), T, 1536, D, E); }
.LBB0_386:
	s_cmp_lt_i32 s30, 4
	s_cselect_b64 s[4:5], -1, 0
	s_add_u32 s46, s28, 0xc800000
	s_addc_u32 s47, s29, 0
	s_and_b64 s[6:7], s[4:5], s[0:1]
	s_andn2_b64 vcc, exec, s[6:7]
	s_cbranch_vccnz .LBB0_425
	s_ashr_i32 s3, s2, 31
	s_cmpk_lt_i32 s2, 0x300
	s_cbranch_scc0 .Lpro_skip_1
	v_readfirstlane_b32 s5, v197
	s_nop 3
	v_lshrrev_b32_e32 v0, 5, v197
	v_lshrrev_b32_e32 v2, 1, v197
	v_and_b32_e32 v0, 4, v0
	v_bfe_u32 v1, v197, 2, 2
	v_and_b32_e32 v11, 24, v2
	v_or3_b32 v0, v0, v1, v11
	v_lshlrev_b32_e32 v1, 4, v197
	v_add_u32_e32 v8, 0x2000, v1
	v_lshrrev_b32_e32 v2, 7, v8
	s_movk_i32 s0, 0xe0
	v_and_b32_e32 v4, 32, v197
	v_and_or_b32 v3, v2, s0, v0
	v_bitop3_b32 v9, v1, v4, 48 bitop3:0x6c
	v_and_b32_e32 v10, 64, v197
	v_bfe_u32 v12, v197, 2, 4
	s_movk_i32 s0, 0xf0
	v_or_b32_e32 v1, v9, v10
	v_and_or_b32 v2, v2, s0, v12
	v_lshl_or_b32 v130, v2, 11, v1
	v_lshrrev_b32_e32 v2, 3, v197
	s_movk_i32 s0, 0x60
	s_add_u32 s61, s28, 0x4a00000
	v_and_or_b32 v0, v2, s0, v0
	s_movk_i32 s0, 0x70
	s_addc_u32 s62, s29, 0
	v_lshl_or_b32 v132, v0, 11, v1
	v_and_or_b32 v0, v2, s0, v12
	s_lshr_b32 s0, s3, 29
	s_add_i32 s0, s2, s0
	s_lshr_b32 s8, s5, 6
	s_ashr_i32 s1, s0, 3
	s_and_b32 s0, s0, -8
	s_lshr_b32 s12, s5, 8
	s_lshl_b32 s63, s8, 10
	s_sub_i32 s0, s2, s0
	s_cmp_lt_i32 s0, 0
	s_movk_i32 s64, 0x61
	s_cselect_b32 s4, s64, 0x60
	s_mul_i32 s0, s4, s0
	s_add_i32 s0, s0, s1
	s_mul_hi_i32 s1, s0, 0x2aaaaaab
	s_lshr_b32 s4, s1, 31
	s_ashr_i32 s1, s1, 3
	s_add_i32 s1, s1, s4
	s_lshl_b32 s9, s1, 3
	s_mul_i32 s1, s1, 48
	s_sub_i32 s0, s0, s1
	s_bfe_i32 s1, s0, 0x80000
	s_bfe_u32 s1, s1, 0x3000c
	s_add_i32 s1, s0, s1
	s_bfe_i32 s4, s1, 0x80000
	s_and_b32 s1, s1, 0xf8
	s_sub_i32 s0, s0, s1
	s_sext_i32_i16 s4, s4
	s_sext_i32_i8 s0, s0
	s_lshr_b32 s4, s4, 3
	s_add_i32 s34, s9, s0
	s_ashr_i32 s35, s34, 31
	s_bfe_i64 s[10:11], s[4:5], 0x100000
	s_lshl_b64 s[0:1], s[34:35], 19
	s_lshl_b64 s[10:11], s[10:11], 19
	s_add_u32 s52, s61, s10
	s_addc_u32 s53, s62, s11
	s_add_i32 s35, s63, 0
	s_add_i32 m0, s35, 0x10000
	v_lshl_or_b32 v128, v3, 11, v1
	global_load_lds_dwordx4 v132, s[52:53]
	s_add_i32 m0, s35, 0x12000
	s_add_u32 s10, s52, 0x40000
	global_load_lds_dwordx4 v128, s[52:53]
	s_addc_u32 s11, s53, 0
	s_add_i32 m0, s35, 0x14000
	v_lshl_or_b32 v134, v0, 11, v1
	global_load_lds_dwordx4 v132, s[10:11]
	s_add_i32 m0, s35, 0x16000
	s_add_u32 s20, s36, s0
	s_addc_u32 s21, s37, s1
	s_add_i32 s65, s35, 0x2000
	global_load_lds_dwordx4 v128, s[10:11]
	s_mov_b32 m0, s35
	s_add_u32 s0, s20, 0x40000
	global_load_lds_dwordx4 v134, s[20:21]
	s_mov_b32 m0, s65
	s_addc_u32 s1, s21, 0
	s_add_i32 s66, s35, 0x4000
	global_load_lds_dwordx4 v130, s[20:21]
	s_mov_b32 m0, s66
	s_add_i32 s67, s35, 0x6000
	global_load_lds_dwordx4 v134, s[0:1]
	s_mov_b32 m0, s67
	v_mov_b32_e32 v137, 0
	global_load_lds_dwordx4 v130, s[0:1]
	s_mov_b32 s98, s12
	s_mov_b32 s99, s4
	s_mov_b32 s100, s8
	v_mov_b32_e32 v240, v10
	v_mov_b32_e32 v241, v11
	v_mov_b32_e32 v242, v12
	v_mov_b32_e32 v243, v8
	v_mov_b32_e32 v244, v9
.Lpro_skip_1:
	s_ashr_i32 s56, s22, 31
	s_mov_b32 s57, s22
	s_mov_b32 s58, -1
	s_mov_b32 s4, 16
	s_waitcnt lgkmcnt(0)
	v_mov_b64_e32 v[0:1], 0x2ff
	s_mov_b64 s[0:1], s[2:3]
	s_mov_b32 s60, -1
	s_mov_b32 s59, -1
	s_mov_b32 s12, -1
	s_branch .LBB0_390

; #define PG8_STAGE(bufoff, gbase, voff) do { _Pragma("unroll") for (int _i = 0; _i < 2; ++_i) \
;         __builtin_amdgcn_global_load_lds((const unsigned*)((const char*)(gbase) + (voff)[_i]), (PG8_LAS unsigned*)(lds + (bufoff) + ldsw + _i * 8192), 16, 0, 0); } while (0)
; #define PG8_WAIT_V(n) asm volatile("s_waitcnt vmcnt(" #n ")" ::: "memory")
; #define PG8_BAR __builtin_amdgcn_s_barrier()
; template <class Epi, class Sched, bool ALIGN_EPI = false, bool SP2 = false>
; __device__ __forceinline__ void gemm_phase(PG8_LAS unsigned char* lds, const Gemm g, const Sched& S, const Epi& E) {
;     ...
;         PG8_STAGE(PG8_SB(0, 0), cB, voffB); PG8_STAGE(PG8_SB(0, 1), cB + hstep, voffB); PG8_STAGE(PG8_SA(0, 0), cA, voffA); PG8_STAGE(PG8_SA(0, 1), cA + hstep, voffA);
;         if (wr == 1) PG8_BAR;
;         PG8_WAIT_V(2); PG8_BAR;
.LBB0_405:
	s_or_b64 exec, exec, s[4:5]
	s_cmpk_lt_i32 s2, 0x300
	v_readfirstlane_b32 s5, v197
	s_waitcnt lgkmcnt(0)
	s_barrier
	s_cbranch_scc0 .LBB0_425
	s_mov_b32 s12, s98
	s_mov_b32 s4, s99
	s_mov_b32 s8, s100
	v_mov_b32_e32 v10, v240
	v_mov_b32_e32 v11, v241
	v_mov_b32_e32 v12, v242
	v_mov_b32_e32 v8, v243
	v_mov_b32_e32 v9, v244
	v_mov_b32_e32 v133, v137
	v_mov_b32_e32 v129, v137
	v_mov_b32_e32 v135, v137
	v_mov_b32_e32 v131, v137
	s_cmp_eq_u32 s12, 1
	s_mov_b32 s68, 0
	v_lshl_add_u64 v[6:7], s[52:53], 0, v[132:133]
	v_lshl_add_u64 v[4:5], s[52:53], 0, v[128:129]
	v_lshl_add_u64 v[0:1], s[20:21], 0, v[134:135]
	s_cselect_b64 s[0:1], -1, 0
	s_cmp_lg_u32 s12, 1
	v_lshl_add_u64 v[2:3], s[20:21], 0, v[130:131]
	s_cbranch_scc1 .LBB0_408
	s_barrier

; #define PG8_STAGE(bufoff, gbase, voff) do { _Pragma("unroll") for (int _i = 0; _i < 2; ++_i) \
;         __builtin_amdgcn_global_load_lds((const unsigned*)((const char*)(gbase) + (voff)[_i]), (PG8_LAS unsigned*)(lds + (bufoff) + ldsw + _i * 8192), 16, 0, 0); } while (0)
; template <class Epi, class Sched, bool ALIGN_EPI = false, bool SP2 = false>
; __device__ __forceinline__ void gemm_phase(PG8_LAS unsigned char* lds, const Gemm g, const Sched& S, const Epi& E) {
;     const int tid = threadIdx.x, wid = __builtin_amdgcn_readfirstlane(tid >> 6), lane = tid & 63, wr = wid >> 2, wc = wid & 3, fr = lane & 15, fq = lane >> 4;
;     const int K = g.K, nt = K / BK;
;     unsigned voffA[2], voffB[2];
; #pragma unroll
;     for (int i = 0; i < 2; ++i) { int R, C; stage_rc(tid * 16 + i * 8192, R, C); const int Rb = Epi::PERM ? ((R & ~31) + perm32(R & 31)) : R;
;         voffA[i] = (unsigned)(R * K + C) * 2u; voffB[i] = (unsigned)(Rb * K + C) * 2u; }
;     const size_t kstep = (size_t)(BK * 2);
;     const size_t hstep = (size_t)HALF * K * 2;
;     const size_t tstep = 2 * hstep;
;     const unsigned ldsw = (unsigned)wid * 1024u;
;     const int aoff = lds_byte(wr * 64 + fr, fq * 8), boff = lds_byte(wc * 32 + fr, fq * 8);
;     ...
;     Unit cur, nxt; int ui = 0;
;     if (!S.next(0, cur)) return;
;     f32x4 acc[2][2][4][2];
; #pragma unroll
;     for (int a = 0; a < 2; ++a)
; #pragma unroll
;         for (int b = 0; b < 2; ++b)
; #pragma unroll
;             for (int m = 0; m < 4; ++m)
; #pragma unroll
;                 for (int n = 0; n < 2; ++n) acc[a][b][m][n] = (f32x4){0.f, 0.f, 0.f, 0.f};
;     bf16x8 At[4][2], B0[2][2], B1[2][2];
;     const char* cA = (const char*)g.A + (size_t)cur.pm * tstep; const char* cB = (const char*)g.Bt + (size_t)cur.pn * tstep;
;     S.a_ready(cur);
;     if constexpr (SP2) {
;         PG8_STAGE(PG8_SB(0, 0), cB, voffB); PG8_STAGE(PG8_SB(0, 1), cB + hstep, voffB); PG8_STAGE(PG8_SA(0, 0), cA, voffA); PG8_STAGE(PG8_SA(0, 1), cA + hstep, voffA);
.LBB0_782:
	s_cmp_lt_i32 s30, 9
	s_cselect_b64 s[0:1], -1, 0
	s_and_b64 s[6:7], s[0:1], s[4:5]
	s_andn2_b64 vcc, exec, s[6:7]
	s_cbranch_vccnz .LBB0_817
	s_ashr_i32 s3, s2, 31
	s_cmpk_lt_i32 s2, 0xb00
	s_cbranch_scc0 .Lpro_skip_2
	v_readfirstlane_b32 s5, v197
	s_nop 3
	v_lshrrev_b32_e32 v0, 5, v197
	v_lshrrev_b32_e32 v2, 1, v197
	v_and_b32_e32 v0, 4, v0
	v_bfe_u32 v1, v197, 2, 2
	v_and_b32_e32 v11, 24, v2
	v_or3_b32 v0, v0, v1, v11
	v_lshlrev_b32_e32 v1, 4, v197
	v_add_u32_e32 v8, 0x2000, v1
	v_lshrrev_b32_e32 v2, 7, v8
	s_movk_i32 s0, 0xe0
	v_and_b32_e32 v4, 32, v197
	v_and_or_b32 v3, v2, s0, v0
	v_bitop3_b32 v9, v1, v4, 48 bitop3:0x6c
	v_and_b32_e32 v10, 64, v197
	v_bfe_u32 v12, v197, 2, 4
	s_movk_i32 s0, 0xf0
	v_or_b32_e32 v1, v9, v10
	v_and_or_b32 v2, v2, s0, v12
	v_lshl_or_b32 v130, v2, 11, v1
	v_lshrrev_b32_e32 v2, 3, v197
	s_movk_i32 s0, 0x60
	s_add_u32 s50, s28, 0x1300000
	v_and_or_b32 v0, v2, s0, v0
	s_movk_i32 s0, 0x70
	s_addc_u32 s51, s29, 0
	v_lshl_or_b32 v132, v0, 11, v1
	v_and_or_b32 v0, v2, s0, v12
	s_lshr_b32 s0, s3, 29
	s_add_i32 s0, s2, s0
	s_lshr_b32 s8, s5, 6
	s_ashr_i32 s1, s0, 3
	s_and_b32 s0, s0, -8
	s_lshr_b32 s12, s5, 8
	s_lshl_b32 s52, s8, 10
	s_sub_i32 s0, s2, s0
	s_cmp_lt_i32 s0, 0
	s_movk_i32 s53, 0x161
	s_cselect_b32 s4, s53, 0x160
	s_mul_i32 s0, s4, s0
	s_add_i32 s0, s0, s1
	s_mul_hi_i32 s1, s0, 0x2e8ba2e9
	s_lshr_b32 s4, s1, 31
	s_ashr_i32 s1, s1, 5
	s_add_i32 s1, s1, s4
	s_lshl_b32 s9, s1, 3
	s_mulk_i32 s1, 0xb0
	s_sub_i32 s0, s0, s1
	s_sext_i32_i16 s1, s0
	s_bfe_u32 s1, s1, 0x3001c
	s_add_i32 s1, s0, s1
	s_sext_i32_i16 s4, s1
	s_and_b32 s1, s1, 0xfff8
	s_sub_i32 s0, s0, s1
	s_sext_i32_i16 s0, s0
	s_lshr_b32 s4, s4, 3
	s_add_i32 s34, s9, s0
	s_ashr_i32 s35, s34, 31
	s_bfe_i64 s[10:11], s[4:5], 0x100000
	s_lshl_b64 s[0:1], s[34:35], 19
	s_lshl_b64 s[10:11], s[10:11], 19
	s_add_u32 s38, s50, s10
	s_addc_u32 s39, s51, s11
	s_add_i32 s35, s52, 0
	s_add_i32 m0, s35, 0x10000
	v_lshl_or_b32 v128, v3, 11, v1
	global_load_lds_dwordx4 v132, s[38:39]
	s_add_i32 m0, s35, 0x12000
	s_add_u32 s10, s38, 0x40000
	global_load_lds_dwordx4 v128, s[38:39]
	s_addc_u32 s11, s39, 0
	s_add_i32 m0, s35, 0x14000
	v_lshl_or_b32 v134, v0, 11, v1
	global_load_lds_dwordx4 v132, s[10:11]
	s_add_i32 m0, s35, 0x16000
	s_add_u32 s20, s36, s0
	s_addc_u32 s21, s37, s1
	s_add_i32 s54, s35, 0x2000
	global_load_lds_dwordx4 v128, s[10:11]
	s_mov_b32 m0, s35
	s_add_u32 s0, s20, 0x40000
	global_load_lds_dwordx4 v134, s[20:21]
	s_mov_b32 m0, s54
	s_addc_u32 s1, s21, 0
	s_add_i32 s55, s35, 0x4000
	global_load_lds_dwordx4 v130, s[20:21]
	s_mov_b32 m0, s55
	s_add_i32 s56, s35, 0x6000
	global_load_lds_dwordx4 v134, s[0:1]
	s_mov_b32 m0, s56
	v_mov_b32_e32 v133, 0
	global_load_lds_dwordx4 v130, s[0:1]
	s_mov_b32 s98, s12
	s_mov_b32 s99, s4
	s_mov_b32 s100, s8
	v_mov_b32_e32 v240, v10
	v_mov_b32_e32 v241, v11
	v_mov_b32_e32 v242, v12
	v_mov_b32_e32 v243, v8
	v_mov_b32_e32 v244, v9
.Lpro_skip_2:
	s_ashr_i32 s33, s22, 31
	s_mov_b32 s46, s22
	s_mov_b32 s47, -1
	s_mov_b32 s4, 16
	s_waitcnt lgkmcnt(0)
	v_mov_b64_e32 v[0:1], 0xaff
	s_mov_b64 s[0:1], s[2:3]
	s_mov_b32 s49, -1
	s_mov_b32 s48, -1
	s_mov_b32 s12, -1
	s_branch .LBB0_786

; #define PG8_STAGE(bufoff, gbase, voff) do { _Pragma("unroll") for (int _i = 0; _i < 2; ++_i) \
;         __builtin_amdgcn_global_load_lds((const unsigned*)((const char*)(gbase) + (voff)[_i]), (PG8_LAS unsigned*)(lds + (bufoff) + ldsw + _i * 8192), 16, 0, 0); } while (0)
; #define PG8_WAIT_V(n) asm volatile("s_waitcnt vmcnt(" #n ")" ::: "memory")
; #define PG8_BAR __builtin_amdgcn_s_barrier()
; template <class Epi, class Sched, bool ALIGN_EPI = false, bool SP2 = false>
; __device__ __forceinline__ void gemm_phase(PG8_LAS unsigned char* lds, const Gemm g, const Sched& S, const Epi& E) {
;     ...
;         PG8_STAGE(PG8_SB(0, 0), cB, voffB); PG8_STAGE(PG8_SB(0, 1), cB + hstep, voffB); PG8_STAGE(PG8_SA(0, 0), cA, voffA); PG8_STAGE(PG8_SA(0, 1), cA + hstep, voffA);
;         if (wr == 1) PG8_BAR;
;         PG8_WAIT_V(2); PG8_BAR;
.LBB0_801:
	s_or_b64 exec, exec, s[4:5]
	s_cmpk_lt_i32 s2, 0xb00
	v_readfirstlane_b32 s5, v197
	s_waitcnt lgkmcnt(0)
	s_barrier
	s_cbranch_scc0 .LBB0_817
	s_mov_b32 s12, s98
	s_mov_b32 s4, s99
	s_mov_b32 s8, s100
	v_mov_b32_e32 v10, v240
	v_mov_b32_e32 v11, v241
	v_mov_b32_e32 v12, v242
	v_mov_b32_e32 v8, v243
	v_mov_b32_e32 v9, v244
	v_mov_b32_e32 v129, v133
	v_mov_b32_e32 v135, v133
	v_mov_b32_e32 v131, v133
	s_cmp_eq_u32 s12, 1
	s_mov_b32 s57, 0
	v_lshl_add_u64 v[6:7], s[38:39], 0, v[132:133]
	v_lshl_add_u64 v[4:5], s[38:39], 0, v[128:129]
	v_lshl_add_u64 v[0:1], s[20:21], 0, v[134:135]
	s_cselect_b64 s[0:1], -1, 0
	s_cmp_lg_u32 s12, 1
	v_lshl_add_u64 v[2:3], s[20:21], 0, v[130:131]
	s_cbranch_scc1 .LBB0_804
	s_barrier

; #define PG8_STAGE(bufoff, gbase, voff) do { _Pragma("unroll") for (int _i = 0; _i < 2; ++_i) \
;         __builtin_amdgcn_global_load_lds((const unsigned*)((const char*)(gbase) + (voff)[_i]), (PG8_LAS unsigned*)(lds + (bufoff) + ldsw + _i * 8192), 16, 0, 0); } while (0)
; template <class Epi, class Sched, bool ALIGN_EPI = false, bool SP2 = false>
; __device__ __forceinline__ void gemm_phase(PG8_LAS unsigned char* lds, const Gemm g, const Sched& S, const Epi& E) {
;     const int tid = threadIdx.x, wid = __builtin_amdgcn_readfirstlane(tid >> 6), lane = tid & 63, wr = wid >> 2, wc = wid & 3, fr = lane & 15, fq = lane >> 4;
;     const int K = g.K, nt = K / BK;
;     unsigned voffA[2], voffB[2];
; #pragma unroll
;     for (int i = 0; i < 2; ++i) { int R, C; stage_rc(tid * 16 + i * 8192, R, C); const int Rb = Epi::PERM ? ((R & ~31) + perm32(R & 31)) : R;
;         voffA[i] = (unsigned)(R * K + C) * 2u; voffB[i] = (unsigned)(Rb * K + C) * 2u; }
;     const size_t kstep = (size_t)(BK * 2);
;     const size_t hstep = (size_t)HALF * K * 2;
;     const size_t tstep = 2 * hstep;
;     const unsigned ldsw = (unsigned)wid * 1024u;
;     const int aoff = lds_byte(wr * 64 + fr, fq * 8), boff = lds_byte(wc * 32 + fr, fq * 8);
;     ...
;     Unit cur, nxt; int ui = 0;
;     if (!S.next(0, cur)) return;
;     f32x4 acc[2][2][4][2];
; #pragma unroll
;     for (int a = 0; a < 2; ++a)
; #pragma unroll
;         for (int b = 0; b < 2; ++b)
; #pragma unroll
;             for (int m = 0; m < 4; ++m)
; #pragma unroll
;                 for (int n = 0; n < 2; ++n) acc[a][b][m][n] = (f32x4){0.f, 0.f, 0.f, 0.f};
;     bf16x8 At[4][2], B0[2][2], B1[2][2];
;     const char* cA = (const char*)g.A + (size_t)cur.pm * tstep; const char* cB = (const char*)g.Bt + (size_t)cur.pn * tstep;
;     S.a_ready(cur);
;     if constexpr (SP2) {
;         PG8_STAGE(PG8_SB(0, 0), cB, voffB); PG8_STAGE(PG8_SB(0, 1), cB + hstep, voffB); PG8_STAGE(PG8_SA(0, 0), cA, voffA); PG8_STAGE(PG8_SA(0, 1), cA + hstep, voffA);
.LBB0_972:
	s_cmp_lt_i32 s30, 11
	s_cselect_b64 s[4:5], -1, 0
	s_and_b64 s[6:7], s[4:5], s[0:1]
	s_andn2_b64 vcc, exec, s[6:7]
	s_cbranch_vccnz .LBB0_1007
	s_ashr_i32 s3, s2, 31
	s_cmpk_lt_i32 s2, 0xb00
	s_cbranch_scc0 .Lpro_skip_3
	v_readfirstlane_b32 s5, v197
	s_nop 3
	v_lshrrev_b32_e32 v0, 5, v197
	v_lshrrev_b32_e32 v2, 1, v197
	v_and_b32_e32 v0, 4, v0
	v_bfe_u32 v1, v197, 2, 2
	v_and_b32_e32 v11, 24, v2
	v_or3_b32 v0, v0, v1, v11
	v_lshlrev_b32_e32 v1, 4, v197
	v_add_u32_e32 v8, 0x2000, v1
	v_lshrrev_b32_e32 v2, 7, v8
	s_movk_i32 s0, 0xe0
	v_and_b32_e32 v4, 32, v197
	v_and_or_b32 v3, v2, s0, v0
	v_bitop3_b32 v9, v1, v4, 48 bitop3:0x6c
	v_and_b32_e32 v10, 64, v197
	v_bfe_u32 v12, v197, 2, 4
	s_movk_i32 s0, 0xf0
	v_or_b32_e32 v1, v9, v10
	v_and_or_b32 v2, v2, s0, v12
	v_lshl_or_b32 v130, v2, 11, v1
	v_lshrrev_b32_e32 v2, 3, v197
	s_movk_i32 s0, 0x60
	s_add_u32 s50, s28, 0x1e00000
	v_and_or_b32 v0, v2, s0, v0
	s_movk_i32 s0, 0x70
	s_addc_u32 s51, s29, 0
	v_lshl_or_b32 v132, v0, 11, v1
	v_and_or_b32 v0, v2, s0, v12
	s_lshr_b32 s0, s3, 29
	s_add_i32 s0, s2, s0
	s_lshr_b32 s8, s5, 6
	s_ashr_i32 s1, s0, 3
	s_and_b32 s0, s0, -8
	s_lshr_b32 s12, s5, 8
	s_lshl_b32 s52, s8, 10
	s_sub_i32 s0, s2, s0
	s_cmp_lt_i32 s0, 0
	s_movk_i32 s53, 0x161
	s_cselect_b32 s4, s53, 0x160
	s_mul_i32 s0, s4, s0
	s_add_i32 s0, s0, s1
	s_mul_hi_i32 s1, s0, 0x2e8ba2e9
	s_lshr_b32 s4, s1, 31
	s_ashr_i32 s1, s1, 5
	s_add_i32 s1, s1, s4
	s_lshl_b32 s9, s1, 3
	s_mulk_i32 s1, 0xb0
	s_sub_i32 s0, s0, s1
	s_sext_i32_i16 s1, s0
	s_bfe_u32 s1, s1, 0x3001c
	s_add_i32 s1, s0, s1
	s_sext_i32_i16 s4, s1
	s_and_b32 s1, s1, 0xfff8
	s_sub_i32 s0, s0, s1
	s_sext_i32_i16 s0, s0
	s_lshr_b32 s4, s4, 3
	s_add_i32 s34, s9, s0
	s_ashr_i32 s35, s34, 31
	s_bfe_i64 s[10:11], s[4:5], 0x100000
	s_lshl_b64 s[0:1], s[34:35], 19
	s_lshl_b64 s[10:11], s[10:11], 19
	s_add_u32 s38, s50, s10
	s_addc_u32 s39, s51, s11
	s_add_i32 s35, s52, 0
	s_add_i32 m0, s35, 0x10000
	v_lshl_or_b32 v128, v3, 11, v1
	global_load_lds_dwordx4 v132, s[38:39]
	s_add_i32 m0, s35, 0x12000
	s_add_u32 s10, s38, 0x40000
	global_load_lds_dwordx4 v128, s[38:39]
	s_addc_u32 s11, s39, 0
	s_add_i32 m0, s35, 0x14000
	v_lshl_or_b32 v134, v0, 11, v1
	global_load_lds_dwordx4 v132, s[10:11]
	s_add_i32 m0, s35, 0x16000
	s_add_u32 s20, s36, s0
	s_addc_u32 s21, s37, s1
	s_add_i32 s54, s35, 0x2000
	global_load_lds_dwordx4 v128, s[10:11]
	s_mov_b32 m0, s35
	s_add_u32 s0, s20, 0x40000
	global_load_lds_dwordx4 v134, s[20:21]
	s_mov_b32 m0, s54
	s_addc_u32 s1, s21, 0
	s_add_i32 s55, s35, 0x4000
	global_load_lds_dwordx4 v130, s[20:21]
	s_mov_b32 m0, s55
	s_add_i32 s56, s35, 0x6000
	global_load_lds_dwordx4 v134, s[0:1]
	s_mov_b32 m0, s56
	v_mov_b32_e32 v133, 0
	global_load_lds_dwordx4 v130, s[0:1]
	s_mov_b32 s98, s12
	s_mov_b32 s99, s4
	s_mov_b32 s100, s8
	v_mov_b32_e32 v240, v10
	v_mov_b32_e32 v241, v11
	v_mov_b32_e32 v242, v12
	v_mov_b32_e32 v243, v8
	v_mov_b32_e32 v244, v9

; #define PG8_STAGE(bufoff, gbase, voff) do { _Pragma("unroll") for (int _i = 0; _i < 2; ++_i) \
;         __builtin_amdgcn_global_load_lds((const unsigned*)((const char*)(gbase) + (voff)[_i]), (PG8_LAS unsigned*)(lds + (bufoff) + ldsw + _i * 8192), 16, 0, 0); } while (0)
; template <class Epi, class Sched, bool ALIGN_EPI = false, bool SP2 = false>
; __device__ __forceinline__ void gemm_phase(PG8_LAS unsigned char* lds, const Gemm g, const Sched& S, const Epi& E) {
;     const int tid = threadIdx.x, wid = __builtin_amdgcn_readfirstlane(tid >> 6), lane = tid & 63, wr = wid >> 2, wc = wid & 3, fr = lane & 15, fq = lane >> 4;
;     const int K = g.K, nt = K / BK;
;     unsigned voffA[2], voffB[2];
; #pragma unroll
;     for (int i = 0; i < 2; ++i) { int R, C; stage_rc(tid * 16 + i * 8192, R, C); const int Rb = Epi::PERM ? ((R & ~31) + perm32(R & 31)) : R;
;         voffA[i] = (unsigned)(R * K + C) * 2u; voffB[i] = (unsigned)(Rb * K + C) * 2u; }
;     const size_t kstep = (size_t)(BK * 2);
;     const size_t hstep = (size_t)HALF * K * 2;
;     const size_t tstep = 2 * hstep;
;     const unsigned ldsw = (unsigned)wid * 1024u;
;     const int aoff = lds_byte(wr * 64 + fr, fq * 8), boff = lds_byte(wc * 32 + fr, fq * 8);
;     ...
;     Unit cur, nxt; int ui = 0;
;     if (!S.next(0, cur)) return;
;     f32x4 acc[2][2][4][2];
; #pragma unroll
;     for (int a = 0; a < 2; ++a)
; #pragma unroll
;         for (int b = 0; b < 2; ++b)
; #pragma unroll
;             for (int m = 0; m < 4; ++m)
; #pragma unroll
;                 for (int n = 0; n < 2; ++n) acc[a][b][m][n] = (f32x4){0.f, 0.f, 0.f, 0.f};
;     bf16x8 At[4][2], B0[2][2], B1[2][2];
;     const char* cA = (const char*)g.A + (size_t)cur.pm * tstep; const char* cB = (const char*)g.Bt + (size_t)cur.pn * tstep;
;     S.a_ready(cur);
;     if constexpr (SP2) {
;         PG8_STAGE(PG8_SB(0, 0), cB, voffB); PG8_STAGE(PG8_SB(0, 1), cB + hstep, voffB); PG8_STAGE(PG8_SA(0, 0), cA, voffA); PG8_STAGE(PG8_SA(0, 1), cA + hstep, voffA);
.LBB0_1712:
	s_cmp_lt_i32 s30, 17
	s_cselect_b64 s[0:1], -1, 0
	s_and_b64 s[6:7], s[0:1], s[4:5]
	s_andn2_b64 vcc, exec, s[6:7]
	s_cbranch_vccnz .LBB0_1747
	s_ashr_i32 s3, s2, 31
	s_cmpk_lt_i32 s2, 0xb00
	s_cbranch_scc0 .Lpro_skip_4
	v_readfirstlane_b32 s5, v197
	s_nop 3
	v_lshrrev_b32_e32 v0, 5, v197
	v_lshrrev_b32_e32 v2, 1, v197
	v_and_b32_e32 v0, 4, v0
	v_bfe_u32 v1, v197, 2, 2
	v_and_b32_e32 v11, 24, v2
	v_or3_b32 v0, v0, v1, v11
	v_lshlrev_b32_e32 v1, 4, v197
	v_add_u32_e32 v8, 0x2000, v1
	v_lshrrev_b32_e32 v2, 7, v8
	s_movk_i32 s0, 0xe0
	v_and_b32_e32 v4, 32, v197
	v_and_or_b32 v3, v2, s0, v0
	v_bitop3_b32 v9, v1, v4, 48 bitop3:0x6c
	v_and_b32_e32 v10, 64, v197
	v_bfe_u32 v12, v197, 2, 4
	s_movk_i32 s0, 0xf0
	v_or_b32_e32 v1, v9, v10
	v_and_or_b32 v2, v2, s0, v12
	v_lshl_or_b32 v130, v2, 11, v1
	v_lshrrev_b32_e32 v2, 3, v197
	s_movk_i32 s0, 0x60
	s_add_u32 s48, s28, 0x2900000
	v_and_or_b32 v0, v2, s0, v0
	s_movk_i32 s0, 0x70
	s_addc_u32 s49, s29, 0
	v_lshl_or_b32 v132, v0, 11, v1
	v_and_or_b32 v0, v2, s0, v12
	s_lshr_b32 s0, s3, 29
	s_add_i32 s0, s2, s0
	s_lshr_b32 s8, s5, 6
	s_ashr_i32 s1, s0, 3
	s_and_b32 s0, s0, -8
	s_lshr_b32 s12, s5, 8
	s_lshl_b32 s50, s8, 10
	s_sub_i32 s0, s2, s0
	s_cmp_lt_i32 s0, 0
	s_movk_i32 s51, 0x161
	s_cselect_b32 s4, s51, 0x160
	s_mul_i32 s0, s4, s0
	s_add_i32 s0, s0, s1
	s_mul_hi_i32 s1, s0, 0x2e8ba2e9
	s_lshr_b32 s4, s1, 31
	s_ashr_i32 s1, s1, 5
	s_add_i32 s1, s1, s4
	s_lshl_b32 s9, s1, 3
	s_mulk_i32 s1, 0xb0
	s_sub_i32 s0, s0, s1
	s_sext_i32_i16 s1, s0
	s_bfe_u32 s1, s1, 0x3001c
	s_add_i32 s1, s0, s1
	s_sext_i32_i16 s4, s1
	s_and_b32 s1, s1, 0xfff8
	s_sub_i32 s0, s0, s1
	s_sext_i32_i16 s0, s0
	s_lshr_b32 s4, s4, 3
	s_add_i32 s34, s9, s0
	s_ashr_i32 s35, s34, 31
	s_bfe_i64 s[10:11], s[4:5], 0x100000
	s_lshl_b64 s[0:1], s[34:35], 19
	s_lshl_b64 s[10:11], s[10:11], 19
	s_add_u32 s38, s48, s10
	s_addc_u32 s39, s49, s11
	s_add_i32 s35, s50, 0
	s_add_i32 m0, s35, 0x10000
	v_lshl_or_b32 v128, v3, 11, v1
	global_load_lds_dwordx4 v132, s[38:39]
	s_add_i32 m0, s35, 0x12000
	s_add_u32 s10, s38, 0x40000
	global_load_lds_dwordx4 v128, s[38:39]
	s_addc_u32 s11, s39, 0
	s_add_i32 m0, s35, 0x14000
	v_lshl_or_b32 v134, v0, 11, v1
	global_load_lds_dwordx4 v132, s[10:11]
	s_add_i32 m0, s35, 0x16000
	s_add_u32 s20, s36, s0
	s_addc_u32 s21, s37, s1
	s_add_i32 s52, s35, 0x2000
	global_load_lds_dwordx4 v128, s[10:11]
	s_mov_b32 m0, s35
	s_add_u32 s0, s20, 0x40000
	global_load_lds_dwordx4 v134, s[20:21]
	s_mov_b32 m0, s52
	s_addc_u32 s1, s21, 0
	s_add_i32 s53, s35, 0x4000
	global_load_lds_dwordx4 v130, s[20:21]
	s_mov_b32 m0, s53
	s_add_i32 s54, s35, 0x6000
	global_load_lds_dwordx4 v134, s[0:1]
	s_mov_b32 m0, s54
	v_mov_b32_e32 v133, 0
	global_load_lds_dwordx4 v130, s[0:1]
	s_mov_b32 s98, s12
	s_mov_b32 s99, s4
	s_mov_b32 s100, s8
	v_mov_b32_e32 v240, v10
	v_mov_b32_e32 v241, v11
	v_mov_b32_e32 v242, v12
	v_mov_b32_e32 v243, v8
	v_mov_b32_e32 v244, v9
.Lpro_skip_4:
	s_ashr_i32 s33, s22, 31
	s_mov_b32 s44, s22
	s_mov_b32 s12, -1
	s_mov_b32 s4, 16
	s_waitcnt lgkmcnt(0)
	v_mov_b64_e32 v[0:1], 0xaff
	s_mov_b64 s[0:1], s[2:3]
	s_mov_b32 s45, -1
	s_mov_b32 s46, -1
	s_mov_b32 s47, -1
	s_branch .LBB0_1716

; #define PG8_STAGE(bufoff, gbase, voff) do { _Pragma("unroll") for (int _i = 0; _i < 2; ++_i) \
;         __builtin_amdgcn_global_load_lds((const unsigned*)((const char*)(gbase) + (voff)[_i]), (PG8_LAS unsigned*)(lds + (bufoff) + ldsw + _i * 8192), 16, 0, 0); } while (0)
; #define PG8_WAIT_V(n) asm volatile("s_waitcnt vmcnt(" #n ")" ::: "memory")
; #define PG8_BAR __builtin_amdgcn_s_barrier()
; template <class Epi, class Sched, bool ALIGN_EPI = false, bool SP2 = false>
; __device__ __forceinline__ void gemm_phase(PG8_LAS unsigned char* lds, const Gemm g, const Sched& S, const Epi& E) {
;     ...
;         PG8_STAGE(PG8_SB(0, 0), cB, voffB); PG8_STAGE(PG8_SB(0, 1), cB + hstep, voffB); PG8_STAGE(PG8_SA(0, 0), cA, voffA); PG8_STAGE(PG8_SA(0, 1), cA + hstep, voffA);
;         if (wr == 1) PG8_BAR;
;         PG8_WAIT_V(2); PG8_BAR;
.LBB0_1731:
	s_or_b64 exec, exec, s[4:5]
	s_cmpk_lt_i32 s2, 0xb00
	v_readfirstlane_b32 s5, v197
	s_waitcnt lgkmcnt(0)
	s_barrier
	s_cbranch_scc0 .LBB0_1747
	s_mov_b32 s12, s98
	s_mov_b32 s4, s99
	s_mov_b32 s8, s100
	v_mov_b32_e32 v10, v240
	v_mov_b32_e32 v11, v241
	v_mov_b32_e32 v12, v242
	v_mov_b32_e32 v8, v243
	v_mov_b32_e32 v9, v244
	v_mov_b32_e32 v129, v133
	v_mov_b32_e32 v135, v133
	v_mov_b32_e32 v131, v133
	s_cmp_eq_u32 s12, 1
	s_mov_b32 s55, 0
	v_lshl_add_u64 v[6:7], s[38:39], 0, v[132:133]
	v_lshl_add_u64 v[4:5], s[38:39], 0, v[128:129]
	v_lshl_add_u64 v[0:1], s[20:21], 0, v[134:135]
	s_cselect_b64 s[0:1], -1, 0
	s_cmp_lg_u32 s12, 1
	v_lshl_add_u64 v[2:3], s[20:21], 0, v[130:131]
	s_cbranch_scc1 .LBB0_1734
	s_barrier
